# HGRN: per-wave 4-token sum(q) reduced in one transposed pass with an unmasked write; POST store address computed once with immediate offsets; on top of batched RWKV output stage
# speedup vs baseline: 1.0063x; 1.0063x over previous
; __device__ __forceinline__ u16 f2bf(float f) { return (u16)(cvt_pk_bf16(f, 0.f) & 0xffffu); }
; __device__ __forceinline__ void phase_hgrn(KP P, int l_, unsigned char* shm) {
;     ...
;             for (int i = 0; i < 4; ++i) { const int tl = wave * 4 + i; const size_t tok = (size_t)b * SEQ + c * T + tl;
;                 const f32x4 oa = *(const f32x4*)(sO + tl * 256 + lane * 4);
;                 const float o = ((oa[0] + oa[1]) + (oa[2] + oa[3])) + sVN[tl * 64 + lane] * sQS[tl];
;                 OC[tok * 512 + h * 128 + half * 64 + lane] = f2bf(o); }
;             if (c + 1 < SEQ / T) HG_PREP();
.LBB0_2172:
	s_waitcnt lgkmcnt(0)
	s_barrier
	s_waitcnt vmcnt(0)
	v_perm_b32 v1, v246, v227, s82
	v_perm_b32 v0, v222, v217, s82
	v_perm_b32 v124, v221, v216, s82
	v_perm_b32 v128, v245, v226, s82
	v_perm_b32 v123, v220, v215, s82
	v_perm_b32 v127, v244, v225, s82
	v_perm_b32 v122, v219, v214, s82
	v_perm_b32 v126, v243, v224, s82
	v_perm_b32 v121, v218, v213, s82
	v_perm_b32 v125, v242, v223, s82
	v_mov_b32_e32 v2, v247
	ds_read_b128 v[158:161], v112 offset:49152
	ds_read_b128 v[162:165], v113 offset:49152
	ds_read_b128 v[166:169], v114 offset:49152
	ds_read_b128 v[170:173], v115 offset:49152
	v_add_u32_e32 v6, v90, v92
	v_add_u32_e32 v7, v90, v96
	v_add_u32_e32 v8, v90, v100
	v_add_u32_e32 v9, v90, v104
	ds_read_b32 v174, v6 offset:40960
	ds_read_b32 v175, v94
	ds_read_b32 v176, v7 offset:40960
	ds_read_b32 v186, v98
	ds_read_b32 v187, v8 offset:40960
	ds_read_b32 v235, v102
	ds_read_b32 v239, v9 offset:40960
	ds_read_b32 v240, v106
	s_lshl_b32 s0, s26, 5
	s_add_u32 s22, s18, s0
	s_addc_u32 s23, s19, 0
	s_and_b64 vcc, exec, s[20:21]
	v_lshl_add_u64 v[10:11], s[22:23], 0, v[40:41]
	s_waitcnt lgkmcnt(0)
	v_add_f32_e32 v4, v158, v159
	v_add_f32_e32 v6, v160, v161
	v_add_f32_e32 v4, v4, v6
	v_fmac_f32_e32 v4, v174, v175
	v_lshlrev_b64 v[6:7], 10, v[10:11]
	v_lshl_add_u64 v[6:7], v[58:59], 0, v[6:7]
	s_nop 0
	v_cvt_pk_bf16_f32 v4, v4, v5
	global_store_short v[6:7], v4, off
	v_add_f32_e32 v8, v162, v163
	v_add_f32_e32 v9, v164, v165
	v_add_f32_e32 v8, v8, v9
	v_fmac_f32_e32 v8, v176, v186
	s_nop 0
	v_cvt_pk_bf16_f32 v8, v8, v5
	global_store_short v[6:7], v8, off offset:1024
	v_add_f32_e32 v4, v166, v167
	v_add_f32_e32 v9, v168, v169
	v_add_f32_e32 v4, v4, v9
	v_fmac_f32_e32 v4, v187, v235
	s_nop 0
	v_cvt_pk_bf16_f32 v4, v4, v5
	global_store_short v[6:7], v4, off offset:2048
	v_add_f32_e32 v8, v170, v171
	v_add_f32_e32 v9, v172, v173
	v_add_f32_e32 v8, v8, v9
	v_fmac_f32_e32 v8, v239, v240
	s_nop 0
	v_cvt_pk_bf16_f32 v8, v8, v5
	global_store_short v[6:7], v8, off offset:3072
	s_cbranch_vccz .LBB0_2157
	v_lshlrev_b32_e32 v4, 16, v121
	v_mul_f32_e32 v6, 0xbfb8aa3b, v4
	v_exp_f32_e32 v6, v6
	v_lshlrev_b32_e32 v7, 16, v122
	v_mul_f32_e32 v8, 0xbfb8aa3b, v7
	v_exp_f32_e32 v8, v8
	v_add_f32_e32 v6, 1.0, v6
	v_rcp_f32_e32 v6, v6
	v_lshlrev_b32_e32 v9, 16, v123
	v_add_f32_e32 v8, 1.0, v8
	v_mul_f32_e32 v9, 0xbfb8aa3b, v9
	v_rcp_f32_e32 v8, v8
	v_mul_f32_e32 v6, v6, v4
	v_exp_f32_e32 v4, v9
	v_lshlrev_b32_e32 v9, 16, v124
	v_mul_f32_e32 v9, 0xbfb8aa3b, v9
	v_exp_f32_e32 v9, v9
	v_mul_f32_e32 v10, v8, v7
	ds_write2st64_b32 v91, v6, v10 offset0:64 offset1:65
	v_fma_f32 v145, v8, v7, v6
	v_add_f32_e32 v4, 1.0, v4
	v_add_f32_e32 v9, 1.0, v9
	v_rcp_f32_e32 v4, v4
	v_rcp_f32_e32 v9, v9
	v_fma_f32 v4, v119, v4, v117
	v_fma_f32 v9, v120, v9, v118
	ds_write2st64_b32 v91, v4, v9 offset1:1
	v_and_b32_e32 v4, 0xffff0000, v0
	v_lshlrev_b32_e32 v9, 16, v0
	v_sub_f32_e32 v9, v9, v4
	ds_write2st64_b32 v93, v9, v4 offset0:128 offset1:160
	v_and_b32_e32 v6, 0xffff0000, v121
	v_mul_f32_e32 v7, 0xbfb8aa3b, v6
	v_exp_f32_e32 v7, v7
	v_and_b32_e32 v10, 0xffff0000, v123
	v_mul_f32_e32 v10, 0xbfb8aa3b, v10
	v_and_b32_e32 v8, 0xffff0000, v122
	v_add_f32_e32 v7, 1.0, v7
	v_rcp_f32_e32 v7, v7
	v_mul_f32_e32 v9, 0xbfb8aa3b, v8
	v_exp_f32_e32 v9, v9
	v_mul_f32_e32 v7, v7, v6
	v_exp_f32_e32 v6, v10
	v_and_b32_e32 v10, 0xffff0000, v124
	v_mul_f32_e32 v10, 0xbfb8aa3b, v10
	v_exp_f32_e32 v10, v10
	v_add_f32_e32 v6, 1.0, v6
	v_add_f32_e32 v9, 1.0, v9
	v_rcp_f32_e32 v6, v6
	v_add_f32_e32 v10, 1.0, v10
	v_rcp_f32_e32 v10, v10
	v_rcp_f32_e32 v9, v9
	v_fma_f32 v6, v119, v6, v117
	v_fma_f32 v10, v120, v10, v118
	v_mul_f32_e32 v11, v9, v8
	ds_write2st64_b32 v95, v6, v10 offset1:1
	v_lshlrev_b32_e32 v6, 16, v1
	ds_write2st64_b32 v95, v7, v11 offset0:64 offset1:65
	v_sub_f32_e32 v4, v4, v6
	v_fma_f32 v146, v9, v8, v7
	ds_write2st64_b32 v97, v4, v6 offset0:128 offset1:160
	v_lshlrev_b32_e32 v4, 16, v125
	v_mul_f32_e32 v7, 0xbfb8aa3b, v4
	v_exp_f32_e32 v7, v7
	v_lshlrev_b32_e32 v10, 16, v127
	v_mul_f32_e32 v10, 0xbfb8aa3b, v10
	v_lshlrev_b32_e32 v8, 16, v126
	v_add_f32_e32 v7, 1.0, v7
	v_rcp_f32_e32 v7, v7
	v_mul_f32_e32 v9, 0xbfb8aa3b, v8
	v_exp_f32_e32 v9, v9
	v_mul_f32_e32 v7, v7, v4
	v_exp_f32_e32 v4, v10
	v_lshlrev_b32_e32 v10, 16, v128
	v_mul_f32_e32 v10, 0xbfb8aa3b, v10
	v_exp_f32_e32 v10, v10
	v_add_f32_e32 v4, 1.0, v4
	v_add_f32_e32 v9, 1.0, v9
	v_rcp_f32_e32 v4, v4
	v_add_f32_e32 v10, 1.0, v10
	v_rcp_f32_e32 v10, v10
	v_rcp_f32_e32 v9, v9
	v_fma_f32 v4, v119, v4, v117
	v_fma_f32 v10, v120, v10, v118
	v_mul_f32_e32 v11, v9, v8
	ds_write2st64_b32 v99, v4, v10 offset1:1
	v_and_b32_e32 v4, 0xffff0000, v1
	ds_write2st64_b32 v99, v7, v11 offset0:64 offset1:65
	v_sub_f32_e32 v6, v6, v4
	v_fma_f32 v147, v9, v8, v7
	ds_write2st64_b32 v101, v6, v4 offset0:128 offset1:160
	v_and_b32_e32 v6, 0xffff0000, v125
	v_mul_f32_e32 v7, 0xbfb8aa3b, v6
	v_exp_f32_e32 v7, v7
	v_and_b32_e32 v10, 0xffff0000, v127
	v_mul_f32_e32 v10, 0xbfb8aa3b, v10
	v_and_b32_e32 v8, 0xffff0000, v126
	v_add_f32_e32 v7, 1.0, v7
	v_rcp_f32_e32 v7, v7
	v_mul_f32_e32 v9, 0xbfb8aa3b, v8
	v_exp_f32_e32 v9, v9
	v_mul_f32_e32 v6, v7, v6
	v_exp_f32_e32 v7, v10
	v_and_b32_e32 v10, 0xffff0000, v128
	v_mul_f32_e32 v10, 0xbfb8aa3b, v10
	v_exp_f32_e32 v10, v10
	v_add_f32_e32 v7, 1.0, v7
	v_add_f32_e32 v9, 1.0, v9
	v_rcp_f32_e32 v7, v7
	v_add_f32_e32 v10, 1.0, v10
	v_rcp_f32_e32 v10, v10
	v_rcp_f32_e32 v9, v9
	v_fma_f32 v7, v119, v7, v117
	v_fma_f32 v10, v120, v10, v118
	v_mul_f32_e32 v11, v9, v8
	ds_write2st64_b32 v103, v7, v10 offset1:1
	v_lshlrev_b32_e32 v7, 16, v2
	ds_write2st64_b32 v103, v6, v11 offset0:64 offset1:65
	v_sub_f32_e32 v4, v4, v7
	v_fma_f32 v148, v9, v8, v6
	ds_write2st64_b32 v105, v4, v7 offset0:128 offset1:160
	v_cndmask_b32_e64 v150, v146, v145, s[60:61]
	v_cndmask_b32_e64 v152, v148, v147, s[60:61]
	v_cndmask_b32_e64 v149, v145, v146, s[60:61]
	v_cndmask_b32_e64 v151, v147, v148, s[60:61]
	v_add_f32_dpp v149, v150, v149 quad_perm:[1,0,3,2] row_mask:0xf bank_mask:0xf bound_ctrl:1
	v_add_f32_dpp v151, v152, v151 quad_perm:[1,0,3,2] row_mask:0xf bank_mask:0xf bound_ctrl:1
	v_cndmask_b32_e64 v150, v151, v149, s[62:63]
	v_cndmask_b32_e64 v149, v149, v151, s[62:63]
	v_and_b32_e32 v152, 3, v228
	v_lshl_add_u32 v152, v152, 2, v94
	v_add_f32_dpp v149, v150, v149 quad_perm:[2,3,0,1] row_mask:0xf bank_mask:0xf bound_ctrl:1
	s_nop 1
	v_add_f32_dpp v149, v149, v149 row_ror:4 row_mask:0xf bank_mask:0xf
	s_nop 1
	v_add_f32_dpp v149, v149, v149 row_ror:8 row_mask:0xf bank_mask:0xf
	v_mov_b32_e32 v150, v149
	s_nop 1
	v_permlane16_swap_b32_e32 v150, v149
	v_add_f32_e32 v149, v149, v150
	v_mov_b32_e32 v150, v149
	s_nop 1
	v_permlane32_swap_b32_e32 v150, v149
	v_add_f32_e32 v149, v149, v150
	ds_write_b32 v152, v149
	s_branch .LBB0_2156
